# code placement pin: v054 with the ten K-loop heads aligned to 64 bytes (s_nop padding in the once-per-unit fallthrough)
# speedup vs baseline: 1.0132x; 1.0132x over previous
.LBB0_322:
	s_add_u32 s13, s26, 0x100
	s_addc_u32 s15, s27, 0
	s_add_u32 s24, s24, 0x40080
	v_mov_b32_e32 v2, 0
	s_addc_u32 s25, s25, 0
	s_mov_b32 s21, -2
	v_mov_b32_e32 v3, v2
	v_mov_b32_e32 v4, v2
	v_mov_b32_e32 v5, v2
	v_mov_b32_e32 v10, v2
	v_mov_b32_e32 v11, v2
	v_mov_b32_e32 v12, v2
	v_mov_b32_e32 v13, v2
	v_mov_b32_e32 v18, v2
	v_mov_b32_e32 v19, v2
	v_mov_b32_e32 v20, v2
	v_mov_b32_e32 v21, v2
	v_mov_b32_e32 v26, v2
	v_mov_b32_e32 v27, v2
	v_mov_b32_e32 v28, v2
	v_mov_b32_e32 v29, v2
	v_mov_b32_e32 v34, v2
	v_mov_b32_e32 v35, v2
	v_mov_b32_e32 v36, v2
	v_mov_b32_e32 v37, v2
	v_mov_b32_e32 v42, v2
	v_mov_b32_e32 v43, v2
	v_mov_b32_e32 v44, v2
	v_mov_b32_e32 v45, v2
	v_mov_b32_e32 v50, v2
	v_mov_b32_e32 v51, v2
	v_mov_b32_e32 v52, v2
	v_mov_b32_e32 v53, v2
	v_mov_b32_e32 v58, v2
	v_mov_b32_e32 v59, v2
	v_mov_b32_e32 v60, v2
	v_mov_b32_e32 v61, v2
	v_mov_b32_e32 v6, v2
	v_mov_b32_e32 v7, v2
	v_mov_b32_e32 v8, v2
	v_mov_b32_e32 v9, v2
	v_mov_b32_e32 v14, v2
	v_mov_b32_e32 v15, v2
	v_mov_b32_e32 v16, v2
	v_mov_b32_e32 v17, v2
	v_mov_b32_e32 v22, v2
	v_mov_b32_e32 v23, v2
	v_mov_b32_e32 v24, v2
	v_mov_b32_e32 v25, v2
	v_mov_b32_e32 v30, v2
	v_mov_b32_e32 v31, v2
	v_mov_b32_e32 v32, v2
	v_mov_b32_e32 v33, v2
	v_mov_b32_e32 v38, v2
	v_mov_b32_e32 v39, v2
	v_mov_b32_e32 v40, v2
	v_mov_b32_e32 v41, v2
	v_mov_b32_e32 v46, v2
	v_mov_b32_e32 v47, v2
	v_mov_b32_e32 v48, v2
	v_mov_b32_e32 v49, v2
	v_mov_b32_e32 v54, v2
	v_mov_b32_e32 v55, v2
	v_mov_b32_e32 v56, v2
	v_mov_b32_e32 v57, v2
	v_mov_b32_e32 v62, v2
	v_mov_b32_e32 v63, v2
	v_mov_b32_e32 v64, v2
	v_mov_b32_e32 v65, v2
	v_mov_b32_e32 v66, v2
	v_mov_b32_e32 v67, v2
	v_mov_b32_e32 v68, v2
	v_mov_b32_e32 v69, v2
	v_mov_b32_e32 v74, v2
	v_mov_b32_e32 v75, v2
	v_mov_b32_e32 v76, v2
	v_mov_b32_e32 v77, v2
	v_mov_b32_e32 v82, v2
	v_mov_b32_e32 v83, v2
	v_mov_b32_e32 v84, v2
	v_mov_b32_e32 v85, v2
	v_mov_b32_e32 v90, v2
	v_mov_b32_e32 v91, v2
	v_mov_b32_e32 v92, v2
	v_mov_b32_e32 v93, v2
	v_mov_b32_e32 v98, v2
	v_mov_b32_e32 v99, v2
	v_mov_b32_e32 v100, v2
	v_mov_b32_e32 v101, v2
	v_mov_b32_e32 v106, v2
	v_mov_b32_e32 v107, v2
	v_mov_b32_e32 v108, v2
	v_mov_b32_e32 v109, v2
	v_mov_b32_e32 v114, v2
	v_mov_b32_e32 v115, v2
	v_mov_b32_e32 v116, v2
	v_mov_b32_e32 v117, v2
	v_mov_b32_e32 v122, v2
	v_mov_b32_e32 v123, v2
	v_mov_b32_e32 v124, v2
	v_mov_b32_e32 v125, v2
	v_mov_b32_e32 v70, v2
	v_mov_b32_e32 v71, v2
	v_mov_b32_e32 v72, v2
	v_mov_b32_e32 v73, v2
	v_mov_b32_e32 v78, v2
	v_mov_b32_e32 v79, v2
	v_mov_b32_e32 v80, v2
	v_mov_b32_e32 v81, v2
	v_mov_b32_e32 v86, v2
	v_mov_b32_e32 v87, v2
	v_mov_b32_e32 v88, v2
	v_mov_b32_e32 v89, v2
	v_mov_b32_e32 v94, v2
	v_mov_b32_e32 v95, v2
	v_mov_b32_e32 v96, v2
	v_mov_b32_e32 v97, v2
	v_mov_b32_e32 v102, v2
	v_mov_b32_e32 v103, v2
	v_mov_b32_e32 v104, v2
	v_mov_b32_e32 v105, v2
	v_mov_b32_e32 v110, v2
	v_mov_b32_e32 v111, v2
	v_mov_b32_e32 v112, v2
	v_mov_b32_e32 v113, v2
	v_mov_b32_e32 v118, v2
	v_mov_b32_e32 v119, v2
	v_mov_b32_e32 v120, v2
	v_mov_b32_e32 v121, v2
	v_mov_b32_e32 v126, v2
	v_mov_b32_e32 v127, v2
	v_mov_b32_e32 v128, v2
	v_mov_b32_e32 v129, v2
	.p2alignl 6, 3212836864

.LBB0_436:
	s_add_u32 s24, s24, 0xc000
	s_addc_u32 s25, s25, 0
	s_add_u32 s80, s26, 0x100
	v_mov_b32_e32 v2, 0
	s_addc_u32 s81, s27, 0
	s_mov_b32 s82, -2
	s_waitcnt lgkmcnt(0)
	v_mov_b32_e32 v3, v2
	v_mov_b32_e32 v4, v2
	v_mov_b32_e32 v5, v2
	v_mov_b32_e32 v6, v2
	v_mov_b32_e32 v7, v2
	v_mov_b32_e32 v8, v2
	v_mov_b32_e32 v9, v2
	v_mov_b32_e32 v18, v2
	v_mov_b32_e32 v19, v2
	v_mov_b32_e32 v20, v2
	v_mov_b32_e32 v21, v2
	v_mov_b32_e32 v22, v2
	v_mov_b32_e32 v23, v2
	v_mov_b32_e32 v24, v2
	v_mov_b32_e32 v25, v2
	v_mov_b32_e32 v34, v2
	v_mov_b32_e32 v35, v2
	v_mov_b32_e32 v36, v2
	v_mov_b32_e32 v37, v2
	v_mov_b32_e32 v38, v2
	v_mov_b32_e32 v39, v2
	v_mov_b32_e32 v40, v2
	v_mov_b32_e32 v41, v2
	v_mov_b32_e32 v50, v2
	v_mov_b32_e32 v51, v2
	v_mov_b32_e32 v52, v2
	v_mov_b32_e32 v53, v2
	v_mov_b32_e32 v54, v2
	v_mov_b32_e32 v55, v2
	v_mov_b32_e32 v56, v2
	v_mov_b32_e32 v57, v2
	v_mov_b32_e32 v10, v2
	v_mov_b32_e32 v11, v2
	v_mov_b32_e32 v12, v2
	v_mov_b32_e32 v13, v2
	v_mov_b32_e32 v14, v2
	v_mov_b32_e32 v15, v2
	v_mov_b32_e32 v16, v2
	v_mov_b32_e32 v17, v2
	v_mov_b32_e32 v26, v2
	v_mov_b32_e32 v27, v2
	v_mov_b32_e32 v28, v2
	v_mov_b32_e32 v29, v2
	v_mov_b32_e32 v30, v2
	v_mov_b32_e32 v31, v2
	v_mov_b32_e32 v32, v2
	v_mov_b32_e32 v33, v2
	v_mov_b32_e32 v42, v2
	v_mov_b32_e32 v43, v2
	v_mov_b32_e32 v44, v2
	v_mov_b32_e32 v45, v2
	v_mov_b32_e32 v46, v2
	v_mov_b32_e32 v47, v2
	v_mov_b32_e32 v48, v2
	v_mov_b32_e32 v49, v2
	v_mov_b32_e32 v58, v2
	v_mov_b32_e32 v59, v2
	v_mov_b32_e32 v60, v2
	v_mov_b32_e32 v61, v2
	v_mov_b32_e32 v62, v2
	v_mov_b32_e32 v63, v2
	v_mov_b32_e32 v64, v2
	v_mov_b32_e32 v65, v2
	v_mov_b32_e32 v66, v2
	v_mov_b32_e32 v67, v2
	v_mov_b32_e32 v68, v2
	v_mov_b32_e32 v69, v2
	v_mov_b32_e32 v70, v2
	v_mov_b32_e32 v71, v2
	v_mov_b32_e32 v72, v2
	v_mov_b32_e32 v73, v2
	v_mov_b32_e32 v82, v2
	v_mov_b32_e32 v83, v2
	v_mov_b32_e32 v84, v2
	v_mov_b32_e32 v85, v2
	v_mov_b32_e32 v86, v2
	v_mov_b32_e32 v87, v2
	v_mov_b32_e32 v88, v2
	v_mov_b32_e32 v89, v2
	v_mov_b32_e32 v98, v2
	v_mov_b32_e32 v99, v2
	v_mov_b32_e32 v100, v2
	v_mov_b32_e32 v101, v2
	v_mov_b32_e32 v102, v2
	v_mov_b32_e32 v103, v2
	v_mov_b32_e32 v104, v2
	v_mov_b32_e32 v105, v2
	v_mov_b32_e32 v130, v2
	v_mov_b32_e32 v131, v2
	v_mov_b32_e32 v132, v2
	v_mov_b32_e32 v133, v2
	v_mov_b32_e32 v134, v2
	v_mov_b32_e32 v135, v2
	v_mov_b32_e32 v136, v2
	v_mov_b32_e32 v137, v2
	v_mov_b32_e32 v74, v2
	v_mov_b32_e32 v75, v2
	v_mov_b32_e32 v76, v2
	v_mov_b32_e32 v77, v2
	v_mov_b32_e32 v78, v2
	v_mov_b32_e32 v79, v2
	v_mov_b32_e32 v80, v2
	v_mov_b32_e32 v81, v2
	v_mov_b32_e32 v90, v2
	v_mov_b32_e32 v91, v2
	v_mov_b32_e32 v92, v2
	v_mov_b32_e32 v93, v2
	v_mov_b32_e32 v94, v2
	v_mov_b32_e32 v95, v2
	v_mov_b32_e32 v96, v2
	v_mov_b32_e32 v97, v2
	v_mov_b32_e32 v106, v2
	v_mov_b32_e32 v107, v2
	v_mov_b32_e32 v108, v2
	v_mov_b32_e32 v109, v2
	v_mov_b32_e32 v110, v2
	v_mov_b32_e32 v111, v2
	v_mov_b32_e32 v112, v2
	v_mov_b32_e32 v113, v2
	v_mov_b32_e32 v146, v2
	v_mov_b32_e32 v147, v2
	v_mov_b32_e32 v148, v2
	v_mov_b32_e32 v149, v2
	v_mov_b32_e32 v150, v2
	v_mov_b32_e32 v151, v2
	v_mov_b32_e32 v152, v2
	v_mov_b32_e32 v153, v2
	.p2alignl 6, 3212836864

.LBB0_642:
	s_add_u32 s21, s60, 0x100
	s_addc_u32 s57, s61, 0
	s_add_u32 s58, s58, 0x80080
	v_mov_b32_e32 v2, 0
	s_addc_u32 s59, s59, 0
	s_mov_b32 s64, -2
	s_waitcnt lgkmcnt(0)
	v_mov_b32_e32 v3, v2
	v_mov_b32_e32 v4, v2
	v_mov_b32_e32 v5, v2
	v_mov_b32_e32 v6, v2
	v_mov_b32_e32 v7, v2
	v_mov_b32_e32 v8, v2
	v_mov_b32_e32 v9, v2
	v_mov_b32_e32 v18, v2
	v_mov_b32_e32 v19, v2
	v_mov_b32_e32 v20, v2
	v_mov_b32_e32 v21, v2
	v_mov_b32_e32 v22, v2
	v_mov_b32_e32 v23, v2
	v_mov_b32_e32 v24, v2
	v_mov_b32_e32 v25, v2
	v_mov_b32_e32 v34, v2
	v_mov_b32_e32 v35, v2
	v_mov_b32_e32 v36, v2
	v_mov_b32_e32 v37, v2
	v_mov_b32_e32 v38, v2
	v_mov_b32_e32 v39, v2
	v_mov_b32_e32 v40, v2
	v_mov_b32_e32 v41, v2
	v_mov_b32_e32 v50, v2
	v_mov_b32_e32 v51, v2
	v_mov_b32_e32 v52, v2
	v_mov_b32_e32 v53, v2
	v_mov_b32_e32 v54, v2
	v_mov_b32_e32 v55, v2
	v_mov_b32_e32 v56, v2
	v_mov_b32_e32 v57, v2
	v_mov_b32_e32 v10, v2
	v_mov_b32_e32 v11, v2
	v_mov_b32_e32 v12, v2
	v_mov_b32_e32 v13, v2
	v_mov_b32_e32 v14, v2
	v_mov_b32_e32 v15, v2
	v_mov_b32_e32 v16, v2
	v_mov_b32_e32 v17, v2
	v_mov_b32_e32 v26, v2
	v_mov_b32_e32 v27, v2
	v_mov_b32_e32 v28, v2
	v_mov_b32_e32 v29, v2
	v_mov_b32_e32 v30, v2
	v_mov_b32_e32 v31, v2
	v_mov_b32_e32 v32, v2
	v_mov_b32_e32 v33, v2
	v_mov_b32_e32 v42, v2
	v_mov_b32_e32 v43, v2
	v_mov_b32_e32 v44, v2
	v_mov_b32_e32 v45, v2
	v_mov_b32_e32 v46, v2
	v_mov_b32_e32 v47, v2
	v_mov_b32_e32 v48, v2
	v_mov_b32_e32 v49, v2
	v_mov_b32_e32 v58, v2
	v_mov_b32_e32 v59, v2
	v_mov_b32_e32 v60, v2
	v_mov_b32_e32 v61, v2
	v_mov_b32_e32 v62, v2
	v_mov_b32_e32 v63, v2
	v_mov_b32_e32 v64, v2
	v_mov_b32_e32 v65, v2
	v_mov_b32_e32 v66, v2
	v_mov_b32_e32 v67, v2
	v_mov_b32_e32 v68, v2
	v_mov_b32_e32 v69, v2
	v_mov_b32_e32 v70, v2
	v_mov_b32_e32 v71, v2
	v_mov_b32_e32 v72, v2
	v_mov_b32_e32 v73, v2
	v_mov_b32_e32 v82, v2
	v_mov_b32_e32 v83, v2
	v_mov_b32_e32 v84, v2
	v_mov_b32_e32 v85, v2
	v_mov_b32_e32 v90, v2
	v_mov_b32_e32 v91, v2
	v_mov_b32_e32 v92, v2
	v_mov_b32_e32 v93, v2
	v_mov_b32_e32 v110, v2
	v_mov_b32_e32 v111, v2
	v_mov_b32_e32 v112, v2
	v_mov_b32_e32 v113, v2
	v_mov_b32_e32 v114, v2
	v_mov_b32_e32 v115, v2
	v_mov_b32_e32 v116, v2
	v_mov_b32_e32 v117, v2
	v_mov_b32_e32 v98, v2
	v_mov_b32_e32 v99, v2
	v_mov_b32_e32 v100, v2
	v_mov_b32_e32 v101, v2
	v_mov_b32_e32 v122, v2
	v_mov_b32_e32 v123, v2
	v_mov_b32_e32 v124, v2
	v_mov_b32_e32 v125, v2
	v_mov_b32_e32 v74, v2
	v_mov_b32_e32 v75, v2
	v_mov_b32_e32 v76, v2
	v_mov_b32_e32 v77, v2
	v_mov_b32_e32 v78, v2
	v_mov_b32_e32 v79, v2
	v_mov_b32_e32 v80, v2
	v_mov_b32_e32 v81, v2
	v_mov_b32_e32 v102, v2
	v_mov_b32_e32 v103, v2
	v_mov_b32_e32 v104, v2
	v_mov_b32_e32 v105, v2
	v_mov_b32_e32 v106, v2
	v_mov_b32_e32 v107, v2
	v_mov_b32_e32 v108, v2
	v_mov_b32_e32 v109, v2
	v_mov_b32_e32 v94, v2
	v_mov_b32_e32 v95, v2
	v_mov_b32_e32 v96, v2
	v_mov_b32_e32 v97, v2
	v_mov_b32_e32 v118, v2
	v_mov_b32_e32 v119, v2
	v_mov_b32_e32 v120, v2
	v_mov_b32_e32 v121, v2
	v_mov_b32_e32 v86, v2
	v_mov_b32_e32 v87, v2
	v_mov_b32_e32 v88, v2
	v_mov_b32_e32 v89, v2
	v_mov_b32_e32 v126, v2
	v_mov_b32_e32 v127, v2
	v_mov_b32_e32 v128, v2
	v_mov_b32_e32 v129, v2
	.p2alignl 6, 3212836864

.LBB0_695:
	s_add_u32 s15, s56, 0x100
	s_addc_u32 s17, s57, 0
	s_add_u32 s26, s26, 0x40080
	v_mov_b32_e32 v2, 0
	s_addc_u32 s27, s27, 0
	s_mov_b32 s60, -2
	v_mov_b32_e32 v3, v2
	v_mov_b32_e32 v4, v2
	v_mov_b32_e32 v5, v2
	v_mov_b32_e32 v6, v2
	v_mov_b32_e32 v7, v2
	v_mov_b32_e32 v8, v2
	v_mov_b32_e32 v9, v2
	v_mov_b32_e32 v10, v2
	v_mov_b32_e32 v11, v2
	v_mov_b32_e32 v12, v2
	v_mov_b32_e32 v13, v2
	v_mov_b32_e32 v14, v2
	v_mov_b32_e32 v15, v2
	v_mov_b32_e32 v16, v2
	v_mov_b32_e32 v17, v2
	v_mov_b32_e32 v18, v2
	v_mov_b32_e32 v19, v2
	v_mov_b32_e32 v20, v2
	v_mov_b32_e32 v21, v2
	v_mov_b32_e32 v22, v2
	v_mov_b32_e32 v23, v2
	v_mov_b32_e32 v24, v2
	v_mov_b32_e32 v25, v2
	v_mov_b32_e32 v26, v2
	v_mov_b32_e32 v27, v2
	v_mov_b32_e32 v28, v2
	v_mov_b32_e32 v29, v2
	v_mov_b32_e32 v30, v2
	v_mov_b32_e32 v31, v2
	v_mov_b32_e32 v32, v2
	v_mov_b32_e32 v33, v2
	v_mov_b32_e32 v66, v2
	v_mov_b32_e32 v67, v2
	v_mov_b32_e32 v68, v2
	v_mov_b32_e32 v69, v2
	v_mov_b32_e32 v70, v2
	v_mov_b32_e32 v71, v2
	v_mov_b32_e32 v72, v2
	v_mov_b32_e32 v73, v2
	v_mov_b32_e32 v74, v2
	v_mov_b32_e32 v75, v2
	v_mov_b32_e32 v76, v2
	v_mov_b32_e32 v77, v2
	v_mov_b32_e32 v78, v2
	v_mov_b32_e32 v79, v2
	v_mov_b32_e32 v80, v2
	v_mov_b32_e32 v81, v2
	v_mov_b32_e32 v82, v2
	v_mov_b32_e32 v83, v2
	v_mov_b32_e32 v84, v2
	v_mov_b32_e32 v85, v2
	v_mov_b32_e32 v86, v2
	v_mov_b32_e32 v87, v2
	v_mov_b32_e32 v88, v2
	v_mov_b32_e32 v89, v2
	v_mov_b32_e32 v90, v2
	v_mov_b32_e32 v91, v2
	v_mov_b32_e32 v92, v2
	v_mov_b32_e32 v93, v2
	v_mov_b32_e32 v94, v2
	v_mov_b32_e32 v95, v2
	v_mov_b32_e32 v96, v2
	v_mov_b32_e32 v97, v2
	v_mov_b32_e32 v34, v2
	v_mov_b32_e32 v35, v2
	v_mov_b32_e32 v36, v2
	v_mov_b32_e32 v37, v2
	v_mov_b32_e32 v38, v2
	v_mov_b32_e32 v39, v2
	v_mov_b32_e32 v40, v2
	v_mov_b32_e32 v41, v2
	v_mov_b32_e32 v42, v2
	v_mov_b32_e32 v43, v2
	v_mov_b32_e32 v44, v2
	v_mov_b32_e32 v45, v2
	v_mov_b32_e32 v46, v2
	v_mov_b32_e32 v47, v2
	v_mov_b32_e32 v48, v2
	v_mov_b32_e32 v49, v2
	v_mov_b32_e32 v50, v2
	v_mov_b32_e32 v51, v2
	v_mov_b32_e32 v52, v2
	v_mov_b32_e32 v53, v2
	v_mov_b32_e32 v54, v2
	v_mov_b32_e32 v55, v2
	v_mov_b32_e32 v56, v2
	v_mov_b32_e32 v57, v2
	v_mov_b32_e32 v58, v2
	v_mov_b32_e32 v59, v2
	v_mov_b32_e32 v60, v2
	v_mov_b32_e32 v61, v2
	v_mov_b32_e32 v62, v2
	v_mov_b32_e32 v63, v2
	v_mov_b32_e32 v64, v2
	v_mov_b32_e32 v65, v2
	v_mov_b32_e32 v98, v2
	v_mov_b32_e32 v99, v2
	v_mov_b32_e32 v100, v2
	v_mov_b32_e32 v101, v2
	v_mov_b32_e32 v102, v2
	v_mov_b32_e32 v103, v2
	v_mov_b32_e32 v104, v2
	v_mov_b32_e32 v105, v2
	v_mov_b32_e32 v106, v2
	v_mov_b32_e32 v107, v2
	v_mov_b32_e32 v108, v2
	v_mov_b32_e32 v109, v2
	v_mov_b32_e32 v110, v2
	v_mov_b32_e32 v111, v2
	v_mov_b32_e32 v112, v2
	v_mov_b32_e32 v113, v2
	v_mov_b32_e32 v114, v2
	v_mov_b32_e32 v115, v2
	v_mov_b32_e32 v116, v2
	v_mov_b32_e32 v117, v2
	v_mov_b32_e32 v118, v2
	v_mov_b32_e32 v119, v2
	v_mov_b32_e32 v120, v2
	v_mov_b32_e32 v121, v2
	v_mov_b32_e32 v122, v2
	v_mov_b32_e32 v123, v2
	v_mov_b32_e32 v124, v2
	v_mov_b32_e32 v125, v2
	v_mov_b32_e32 v126, v2
	v_mov_b32_e32 v127, v2
	v_mov_b32_e32 v128, v2
	v_mov_b32_e32 v129, v2
	.p2alignl 6, 3212836864

.LBB0_967:
	s_add_i32 s56, s9, -2
	s_add_u32 s74, s24, 0x100
	s_addc_u32 s75, s25, 0
	s_add_u32 s22, s22, 0x80080
	s_addc_u32 s23, s23, 0
	s_mov_b32 s24, 0
	.p2alignl 6, 3212836864

.LBB0_1210:
	s_add_u32 s25, s58, 0x100
	s_addc_u32 s62, s59, 0
	s_add_u32 s56, s56, 0x80080
	v_mov_b32_e32 v2, 0
	s_addc_u32 s57, s57, 0
	s_mov_b32 s78, -2
	s_waitcnt lgkmcnt(0)
	v_mov_b32_e32 v3, v2
	v_mov_b32_e32 v4, v2
	v_mov_b32_e32 v5, v2
	v_mov_b32_e32 v6, v2
	v_mov_b32_e32 v7, v2
	v_mov_b32_e32 v8, v2
	v_mov_b32_e32 v9, v2
	v_mov_b32_e32 v18, v2
	v_mov_b32_e32 v19, v2
	v_mov_b32_e32 v20, v2
	v_mov_b32_e32 v21, v2
	v_mov_b32_e32 v22, v2
	v_mov_b32_e32 v23, v2
	v_mov_b32_e32 v24, v2
	v_mov_b32_e32 v25, v2
	v_mov_b32_e32 v34, v2
	v_mov_b32_e32 v35, v2
	v_mov_b32_e32 v36, v2
	v_mov_b32_e32 v37, v2
	v_mov_b32_e32 v38, v2
	v_mov_b32_e32 v39, v2
	v_mov_b32_e32 v40, v2
	v_mov_b32_e32 v41, v2
	v_mov_b32_e32 v50, v2
	v_mov_b32_e32 v51, v2
	v_mov_b32_e32 v52, v2
	v_mov_b32_e32 v53, v2
	v_mov_b32_e32 v54, v2
	v_mov_b32_e32 v55, v2
	v_mov_b32_e32 v56, v2
	v_mov_b32_e32 v57, v2
	v_mov_b32_e32 v10, v2
	v_mov_b32_e32 v11, v2
	v_mov_b32_e32 v12, v2
	v_mov_b32_e32 v13, v2
	v_mov_b32_e32 v14, v2
	v_mov_b32_e32 v15, v2
	v_mov_b32_e32 v16, v2
	v_mov_b32_e32 v17, v2
	v_mov_b32_e32 v26, v2
	v_mov_b32_e32 v27, v2
	v_mov_b32_e32 v28, v2
	v_mov_b32_e32 v29, v2
	v_mov_b32_e32 v30, v2
	v_mov_b32_e32 v31, v2
	v_mov_b32_e32 v32, v2
	v_mov_b32_e32 v33, v2
	v_mov_b32_e32 v42, v2
	v_mov_b32_e32 v43, v2
	v_mov_b32_e32 v44, v2
	v_mov_b32_e32 v45, v2
	v_mov_b32_e32 v46, v2
	v_mov_b32_e32 v47, v2
	v_mov_b32_e32 v48, v2
	v_mov_b32_e32 v49, v2
	v_mov_b32_e32 v58, v2
	v_mov_b32_e32 v59, v2
	v_mov_b32_e32 v60, v2
	v_mov_b32_e32 v61, v2
	v_mov_b32_e32 v62, v2
	v_mov_b32_e32 v63, v2
	v_mov_b32_e32 v64, v2
	v_mov_b32_e32 v65, v2
	v_mov_b32_e32 v66, v2
	v_mov_b32_e32 v67, v2
	v_mov_b32_e32 v68, v2
	v_mov_b32_e32 v69, v2
	v_mov_b32_e32 v70, v2
	v_mov_b32_e32 v71, v2
	v_mov_b32_e32 v72, v2
	v_mov_b32_e32 v73, v2
	v_mov_b32_e32 v82, v2
	v_mov_b32_e32 v83, v2
	v_mov_b32_e32 v84, v2
	v_mov_b32_e32 v85, v2
	v_mov_b32_e32 v86, v2
	v_mov_b32_e32 v87, v2
	v_mov_b32_e32 v88, v2
	v_mov_b32_e32 v89, v2
	v_mov_b32_e32 v98, v2
	v_mov_b32_e32 v99, v2
	v_mov_b32_e32 v100, v2
	v_mov_b32_e32 v101, v2
	v_mov_b32_e32 v102, v2
	v_mov_b32_e32 v103, v2
	v_mov_b32_e32 v104, v2
	v_mov_b32_e32 v105, v2
	v_mov_b32_e32 v122, v2
	v_mov_b32_e32 v123, v2
	v_mov_b32_e32 v124, v2
	v_mov_b32_e32 v125, v2
	v_mov_b32_e32 v126, v2
	v_mov_b32_e32 v127, v2
	v_mov_b32_e32 v128, v2
	v_mov_b32_e32 v129, v2
	v_mov_b32_e32 v74, v2
	v_mov_b32_e32 v75, v2
	v_mov_b32_e32 v76, v2
	v_mov_b32_e32 v77, v2
	v_mov_b32_e32 v78, v2
	v_mov_b32_e32 v79, v2
	v_mov_b32_e32 v80, v2
	v_mov_b32_e32 v81, v2
	v_mov_b32_e32 v90, v2
	v_mov_b32_e32 v91, v2
	v_mov_b32_e32 v92, v2
	v_mov_b32_e32 v93, v2
	v_mov_b32_e32 v94, v2
	v_mov_b32_e32 v95, v2
	v_mov_b32_e32 v96, v2
	v_mov_b32_e32 v97, v2
	v_mov_b32_e32 v106, v2
	v_mov_b32_e32 v107, v2
	v_mov_b32_e32 v108, v2
	v_mov_b32_e32 v109, v2
	v_mov_b32_e32 v114, v2
	v_mov_b32_e32 v115, v2
	v_mov_b32_e32 v116, v2
	v_mov_b32_e32 v117, v2
	v_mov_b32_e32 v130, v2
	v_mov_b32_e32 v131, v2
	v_mov_b32_e32 v132, v2
	v_mov_b32_e32 v133, v2
	v_mov_b32_e32 v134, v2
	v_mov_b32_e32 v135, v2
	v_mov_b32_e32 v136, v2
	v_mov_b32_e32 v137, v2
	.p2alignl 6, 3212836864

.LBB0_1445:
	s_add_u32 s26, s26, 0xc000
	s_addc_u32 s27, s27, 0
	s_add_u32 s82, s56, 0x100
	v_mov_b32_e32 v2, 0
	s_addc_u32 s83, s57, 0
	s_mov_b32 s84, -2
	s_waitcnt lgkmcnt(0)
	v_mov_b32_e32 v3, v2
	v_mov_b32_e32 v4, v2
	v_mov_b32_e32 v5, v2
	v_mov_b32_e32 v6, v2
	v_mov_b32_e32 v7, v2
	v_mov_b32_e32 v8, v2
	v_mov_b32_e32 v9, v2
	v_mov_b32_e32 v18, v2
	v_mov_b32_e32 v19, v2
	v_mov_b32_e32 v20, v2
	v_mov_b32_e32 v21, v2
	v_mov_b32_e32 v22, v2
	v_mov_b32_e32 v23, v2
	v_mov_b32_e32 v24, v2
	v_mov_b32_e32 v25, v2
	v_mov_b32_e32 v34, v2
	v_mov_b32_e32 v35, v2
	v_mov_b32_e32 v36, v2
	v_mov_b32_e32 v37, v2
	v_mov_b32_e32 v38, v2
	v_mov_b32_e32 v39, v2
	v_mov_b32_e32 v40, v2
	v_mov_b32_e32 v41, v2
	v_mov_b32_e32 v50, v2
	v_mov_b32_e32 v51, v2
	v_mov_b32_e32 v52, v2
	v_mov_b32_e32 v53, v2
	v_mov_b32_e32 v54, v2
	v_mov_b32_e32 v55, v2
	v_mov_b32_e32 v56, v2
	v_mov_b32_e32 v57, v2
	v_mov_b32_e32 v10, v2
	v_mov_b32_e32 v11, v2
	v_mov_b32_e32 v12, v2
	v_mov_b32_e32 v13, v2
	v_mov_b32_e32 v14, v2
	v_mov_b32_e32 v15, v2
	v_mov_b32_e32 v16, v2
	v_mov_b32_e32 v17, v2
	v_mov_b32_e32 v26, v2
	v_mov_b32_e32 v27, v2
	v_mov_b32_e32 v28, v2
	v_mov_b32_e32 v29, v2
	v_mov_b32_e32 v30, v2
	v_mov_b32_e32 v31, v2
	v_mov_b32_e32 v32, v2
	v_mov_b32_e32 v33, v2
	v_mov_b32_e32 v42, v2
	v_mov_b32_e32 v43, v2
	v_mov_b32_e32 v44, v2
	v_mov_b32_e32 v45, v2
	v_mov_b32_e32 v46, v2
	v_mov_b32_e32 v47, v2
	v_mov_b32_e32 v48, v2
	v_mov_b32_e32 v49, v2
	v_mov_b32_e32 v58, v2
	v_mov_b32_e32 v59, v2
	v_mov_b32_e32 v60, v2
	v_mov_b32_e32 v61, v2
	v_mov_b32_e32 v62, v2
	v_mov_b32_e32 v63, v2
	v_mov_b32_e32 v64, v2
	v_mov_b32_e32 v65, v2
	v_mov_b32_e32 v66, v2
	v_mov_b32_e32 v67, v2
	v_mov_b32_e32 v68, v2
	v_mov_b32_e32 v69, v2
	v_mov_b32_e32 v70, v2
	v_mov_b32_e32 v71, v2
	v_mov_b32_e32 v72, v2
	v_mov_b32_e32 v73, v2
	v_mov_b32_e32 v82, v2
	v_mov_b32_e32 v83, v2
	v_mov_b32_e32 v84, v2
	v_mov_b32_e32 v85, v2
	v_mov_b32_e32 v86, v2
	v_mov_b32_e32 v87, v2
	v_mov_b32_e32 v88, v2
	v_mov_b32_e32 v89, v2
	v_mov_b32_e32 v98, v2
	v_mov_b32_e32 v99, v2
	v_mov_b32_e32 v100, v2
	v_mov_b32_e32 v101, v2
	v_mov_b32_e32 v102, v2
	v_mov_b32_e32 v103, v2
	v_mov_b32_e32 v104, v2
	v_mov_b32_e32 v105, v2
	v_mov_b32_e32 v122, v2
	v_mov_b32_e32 v123, v2
	v_mov_b32_e32 v124, v2
	v_mov_b32_e32 v125, v2
	v_mov_b32_e32 v126, v2
	v_mov_b32_e32 v127, v2
	v_mov_b32_e32 v128, v2
	v_mov_b32_e32 v129, v2
	v_mov_b32_e32 v74, v2
	v_mov_b32_e32 v75, v2
	v_mov_b32_e32 v76, v2
	v_mov_b32_e32 v77, v2
	v_mov_b32_e32 v78, v2
	v_mov_b32_e32 v79, v2
	v_mov_b32_e32 v80, v2
	v_mov_b32_e32 v81, v2
	v_mov_b32_e32 v90, v2
	v_mov_b32_e32 v91, v2
	v_mov_b32_e32 v92, v2
	v_mov_b32_e32 v93, v2
	v_mov_b32_e32 v94, v2
	v_mov_b32_e32 v95, v2
	v_mov_b32_e32 v96, v2
	v_mov_b32_e32 v97, v2
	v_mov_b32_e32 v106, v2
	v_mov_b32_e32 v107, v2
	v_mov_b32_e32 v108, v2
	v_mov_b32_e32 v109, v2
	v_mov_b32_e32 v114, v2
	v_mov_b32_e32 v115, v2
	v_mov_b32_e32 v116, v2
	v_mov_b32_e32 v117, v2
	v_mov_b32_e32 v130, v2
	v_mov_b32_e32 v131, v2
	v_mov_b32_e32 v132, v2
	v_mov_b32_e32 v133, v2
	v_mov_b32_e32 v134, v2
	v_mov_b32_e32 v135, v2
	v_mov_b32_e32 v136, v2
	v_mov_b32_e32 v137, v2
	.p2alignl 6, 3212836864

.LBB0_1573:
	v_mov_b32_e32 v2, 0
	s_mov_b32 s60, 0
	s_mov_b64 s[56:57], -1
	s_mov_b64 s[58:59], 0
	v_mov_b32_e32 v3, v2
	v_mov_b32_e32 v4, v2
	v_mov_b32_e32 v5, v2
	v_mov_b32_e32 v6, v2
	v_mov_b32_e32 v7, v2
	v_mov_b32_e32 v8, v2
	v_mov_b32_e32 v9, v2
	v_mov_b32_e32 v10, v2
	v_mov_b32_e32 v11, v2
	v_mov_b32_e32 v12, v2
	v_mov_b32_e32 v13, v2
	v_mov_b32_e32 v18, v2
	v_mov_b32_e32 v19, v2
	v_mov_b32_e32 v20, v2
	v_mov_b32_e32 v21, v2
	v_mov_b32_e32 v26, v2
	v_mov_b32_e32 v27, v2
	v_mov_b32_e32 v28, v2
	v_mov_b32_e32 v29, v2
	v_mov_b32_e32 v34, v2
	v_mov_b32_e32 v35, v2
	v_mov_b32_e32 v36, v2
	v_mov_b32_e32 v37, v2
	v_mov_b32_e32 v42, v2
	v_mov_b32_e32 v43, v2
	v_mov_b32_e32 v44, v2
	v_mov_b32_e32 v45, v2
	v_mov_b32_e32 v50, v2
	v_mov_b32_e32 v51, v2
	v_mov_b32_e32 v52, v2
	v_mov_b32_e32 v53, v2
	v_mov_b32_e32 v14, v2
	v_mov_b32_e32 v15, v2
	v_mov_b32_e32 v16, v2
	v_mov_b32_e32 v17, v2
	v_mov_b32_e32 v22, v2
	v_mov_b32_e32 v23, v2
	v_mov_b32_e32 v24, v2
	v_mov_b32_e32 v25, v2
	v_mov_b32_e32 v30, v2
	v_mov_b32_e32 v31, v2
	v_mov_b32_e32 v32, v2
	v_mov_b32_e32 v33, v2
	v_mov_b32_e32 v38, v2
	v_mov_b32_e32 v39, v2
	v_mov_b32_e32 v40, v2
	v_mov_b32_e32 v41, v2
	v_mov_b32_e32 v46, v2
	v_mov_b32_e32 v47, v2
	v_mov_b32_e32 v48, v2
	v_mov_b32_e32 v49, v2
	v_mov_b32_e32 v54, v2
	v_mov_b32_e32 v55, v2
	v_mov_b32_e32 v56, v2
	v_mov_b32_e32 v57, v2
	v_mov_b32_e32 v58, v2
	v_mov_b32_e32 v59, v2
	v_mov_b32_e32 v60, v2
	v_mov_b32_e32 v61, v2
	v_mov_b32_e32 v62, v2
	v_mov_b32_e32 v63, v2
	v_mov_b32_e32 v64, v2
	v_mov_b32_e32 v65, v2
	v_mov_b32_e32 v66, v2
	v_mov_b32_e32 v67, v2
	v_mov_b32_e32 v68, v2
	v_mov_b32_e32 v69, v2
	v_mov_b32_e32 v70, v2
	v_mov_b32_e32 v71, v2
	v_mov_b32_e32 v72, v2
	v_mov_b32_e32 v73, v2
	v_mov_b32_e32 v74, v2
	v_mov_b32_e32 v75, v2
	v_mov_b32_e32 v76, v2
	v_mov_b32_e32 v77, v2
	v_mov_b32_e32 v82, v2
	v_mov_b32_e32 v83, v2
	v_mov_b32_e32 v84, v2
	v_mov_b32_e32 v85, v2
	v_mov_b32_e32 v90, v2
	v_mov_b32_e32 v91, v2
	v_mov_b32_e32 v92, v2
	v_mov_b32_e32 v93, v2
	v_mov_b32_e32 v98, v2
	v_mov_b32_e32 v99, v2
	v_mov_b32_e32 v100, v2
	v_mov_b32_e32 v101, v2
	v_mov_b32_e32 v106, v2
	v_mov_b32_e32 v107, v2
	v_mov_b32_e32 v108, v2
	v_mov_b32_e32 v109, v2
	v_mov_b32_e32 v114, v2
	v_mov_b32_e32 v115, v2
	v_mov_b32_e32 v116, v2
	v_mov_b32_e32 v117, v2
	v_mov_b32_e32 v78, v2
	v_mov_b32_e32 v79, v2
	v_mov_b32_e32 v80, v2
	v_mov_b32_e32 v81, v2
	v_mov_b32_e32 v86, v2
	v_mov_b32_e32 v87, v2
	v_mov_b32_e32 v88, v2
	v_mov_b32_e32 v89, v2
	v_mov_b32_e32 v94, v2
	v_mov_b32_e32 v95, v2
	v_mov_b32_e32 v96, v2
	v_mov_b32_e32 v97, v2
	v_mov_b32_e32 v102, v2
	v_mov_b32_e32 v103, v2
	v_mov_b32_e32 v104, v2
	v_mov_b32_e32 v105, v2
	v_mov_b32_e32 v110, v2
	v_mov_b32_e32 v111, v2
	v_mov_b32_e32 v112, v2
	v_mov_b32_e32 v113, v2
	v_mov_b32_e32 v118, v2
	v_mov_b32_e32 v119, v2
	v_mov_b32_e32 v120, v2
	v_mov_b32_e32 v121, v2
	v_mov_b32_e32 v122, v2
	v_mov_b32_e32 v123, v2
	v_mov_b32_e32 v124, v2
	v_mov_b32_e32 v125, v2
	v_mov_b32_e32 v126, v2
	v_mov_b32_e32 v127, v2
	v_mov_b32_e32 v128, v2
	v_mov_b32_e32 v129, v2
	.p2alignl 6, 3212836864

.LBB0_1614:
	s_add_u32 s25, s66, 0x100
	s_addc_u32 s26, s67, 0
	s_add_u32 s64, s64, 0x40080
	v_mov_b32_e32 v2, 0
	s_addc_u32 s65, s65, 0
	s_mov_b32 s27, -2
	s_waitcnt lgkmcnt(0)
	v_mov_b32_e32 v3, v2
	v_mov_b32_e32 v4, v2
	v_mov_b32_e32 v5, v2
	v_mov_b32_e32 v6, v2
	v_mov_b32_e32 v7, v2
	v_mov_b32_e32 v8, v2
	v_mov_b32_e32 v9, v2
	v_mov_b32_e32 v10, v2
	v_mov_b32_e32 v11, v2
	v_mov_b32_e32 v12, v2
	v_mov_b32_e32 v13, v2
	v_mov_b32_e32 v14, v2
	v_mov_b32_e32 v15, v2
	v_mov_b32_e32 v16, v2
	v_mov_b32_e32 v17, v2
	v_mov_b32_e32 v18, v2
	v_mov_b32_e32 v19, v2
	v_mov_b32_e32 v20, v2
	v_mov_b32_e32 v21, v2
	v_mov_b32_e32 v22, v2
	v_mov_b32_e32 v23, v2
	v_mov_b32_e32 v24, v2
	v_mov_b32_e32 v25, v2
	v_mov_b32_e32 v26, v2
	v_mov_b32_e32 v27, v2
	v_mov_b32_e32 v28, v2
	v_mov_b32_e32 v29, v2
	v_mov_b32_e32 v30, v2
	v_mov_b32_e32 v31, v2
	v_mov_b32_e32 v32, v2
	v_mov_b32_e32 v33, v2
	v_mov_b32_e32 v34, v2
	v_mov_b32_e32 v35, v2
	v_mov_b32_e32 v36, v2
	v_mov_b32_e32 v37, v2
	v_mov_b32_e32 v38, v2
	v_mov_b32_e32 v39, v2
	v_mov_b32_e32 v40, v2
	v_mov_b32_e32 v41, v2
	v_mov_b32_e32 v42, v2
	v_mov_b32_e32 v43, v2
	v_mov_b32_e32 v44, v2
	v_mov_b32_e32 v45, v2
	v_mov_b32_e32 v46, v2
	v_mov_b32_e32 v47, v2
	v_mov_b32_e32 v48, v2
	v_mov_b32_e32 v49, v2
	v_mov_b32_e32 v50, v2
	v_mov_b32_e32 v51, v2
	v_mov_b32_e32 v52, v2
	v_mov_b32_e32 v53, v2
	v_mov_b32_e32 v54, v2
	v_mov_b32_e32 v55, v2
	v_mov_b32_e32 v56, v2
	v_mov_b32_e32 v57, v2
	v_mov_b32_e32 v58, v2
	v_mov_b32_e32 v59, v2
	v_mov_b32_e32 v60, v2
	v_mov_b32_e32 v61, v2
	v_mov_b32_e32 v62, v2
	v_mov_b32_e32 v63, v2
	v_mov_b32_e32 v64, v2
	v_mov_b32_e32 v65, v2
	v_mov_b32_e32 v82, v2
	v_mov_b32_e32 v83, v2
	v_mov_b32_e32 v84, v2
	v_mov_b32_e32 v85, v2
	v_mov_b32_e32 v86, v2
	v_mov_b32_e32 v87, v2
	v_mov_b32_e32 v88, v2
	v_mov_b32_e32 v89, v2
	v_mov_b32_e32 v90, v2
	v_mov_b32_e32 v91, v2
	v_mov_b32_e32 v92, v2
	v_mov_b32_e32 v93, v2
	v_mov_b32_e32 v94, v2
	v_mov_b32_e32 v95, v2
	v_mov_b32_e32 v96, v2
	v_mov_b32_e32 v97, v2
	v_mov_b32_e32 v98, v2
	v_mov_b32_e32 v99, v2
	v_mov_b32_e32 v100, v2
	v_mov_b32_e32 v101, v2
	v_mov_b32_e32 v102, v2
	v_mov_b32_e32 v103, v2
	v_mov_b32_e32 v104, v2
	v_mov_b32_e32 v105, v2
	v_mov_b32_e32 v106, v2
	v_mov_b32_e32 v107, v2
	v_mov_b32_e32 v108, v2
	v_mov_b32_e32 v109, v2
	v_mov_b32_e32 v110, v2
	v_mov_b32_e32 v111, v2
	v_mov_b32_e32 v112, v2
	v_mov_b32_e32 v113, v2
	v_mov_b32_e32 v74, v2
	v_mov_b32_e32 v75, v2
	v_mov_b32_e32 v76, v2
	v_mov_b32_e32 v77, v2
	v_mov_b32_e32 v78, v2
	v_mov_b32_e32 v79, v2
	v_mov_b32_e32 v80, v2
	v_mov_b32_e32 v81, v2
	v_mov_b32_e32 v114, v2
	v_mov_b32_e32 v115, v2
	v_mov_b32_e32 v116, v2
	v_mov_b32_e32 v117, v2
	v_mov_b32_e32 v118, v2
	v_mov_b32_e32 v119, v2
	v_mov_b32_e32 v120, v2
	v_mov_b32_e32 v121, v2
	v_mov_b32_e32 v122, v2
	v_mov_b32_e32 v123, v2
	v_mov_b32_e32 v124, v2
	v_mov_b32_e32 v125, v2
	v_mov_b32_e32 v126, v2
	v_mov_b32_e32 v127, v2
	v_mov_b32_e32 v128, v2
	v_mov_b32_e32 v129, v2
	v_mov_b32_e32 v130, v2
	v_mov_b32_e32 v131, v2
	v_mov_b32_e32 v132, v2
	v_mov_b32_e32 v133, v2
	v_mov_b32_e32 v134, v2
	v_mov_b32_e32 v135, v2
	v_mov_b32_e32 v136, v2
	v_mov_b32_e32 v137, v2
	.p2alignl 6, 3212836864
